# y stores plain instead of nt (on top of stack6)
# speedup vs baseline: 1.0210x; 1.0174x over previous
.LBB0_530:
	v_lshl_add_u64 v[130:131], v[130:131], 2, s[10:11]
	global_load_dword v182, v[130:131], off sc1
	global_load_dword v183, v[130:131], off offset:64 sc1
	global_load_dword v184, v[130:131], off offset:128 sc1
	global_load_dword v185, v[130:131], off offset:192 sc1
	global_load_dword v186, v[130:131], off offset:512 sc1
	global_load_dword v187, v[130:131], off offset:576 sc1
	global_load_dword v188, v[130:131], off offset:640 sc1
	global_load_dword v189, v[130:131], off offset:704 sc1
	v_mov_b32_e32 v178, 0x3727c5ac
	v_lshl_add_u64 v[132:133], s[66:67], 0, v[132:133]
	v_lshlrev_b64 v[128:129], 2, v[128:129]
	v_lshl_add_u64 v[132:133], v[132:133], 0, v[128:129]
	v_lshl_add_u64 v[136:137], v[136:137], 2, s[10:11]
	s_waitcnt vmcnt(0)
	v_mov_b32_e32 v170, v182
	v_fmamk_f32 v170, v170, 0x3a800000, v178
	v_rsq_f32_e32 v170, v170
	s_nop 0
	v_pk_mul_f32 v[124:125], v[124:125], v[170:171] op_sel_hi:[1,0]
	v_pk_mul_f32 v[126:127], v[126:127], v[170:171] op_sel_hi:[1,0]
	v_pk_mul_f32 v[120:121], v[120:121], v[170:171] op_sel_hi:[1,0]
	v_pk_mul_f32 v[122:123], v[122:123], v[170:171] op_sel_hi:[1,0]
	v_pk_mul_f32 v[172:173], v[116:117], v[170:171] op_sel_hi:[1,0]
	v_pk_mul_f32 v[174:175], v[118:119], v[170:171] op_sel_hi:[1,0]
	v_pk_mul_f32 v[176:177], v[112:113], v[170:171] op_sel_hi:[1,0]
	v_pk_mul_f32 v[170:171], v[114:115], v[170:171] op_sel_hi:[1,0]
	v_pk_mul_f32 v[114:115], v[14:15], v[126:127]
	v_pk_mul_f32 v[112:113], v[12:13], v[124:125]
	v_pk_mul_f32 v[118:119], v[10:11], v[122:123]
	v_pk_mul_f32 v[116:117], v[8:9], v[120:121]
	v_pk_mul_f32 v[122:123], v[6:7], v[174:175]
	v_pk_mul_f32 v[120:121], v[4:5], v[172:173]
	v_pk_mul_f32 v[126:127], v[2:3], v[170:171]
	v_pk_mul_f32 v[124:125], v[0:1], v[176:177]
	global_store_dwordx4 v[132:133], v[112:115], off
	global_store_dwordx4 v[132:133], v[116:119], off offset:64
	global_store_dwordx4 v[132:133], v[120:123], off offset:512
	global_store_dwordx4 v[132:133], v[124:127], off offset:576
	v_mov_b32_e32 v112, v183
	v_lshl_add_u64 v[114:115], s[66:67], 0, v[134:135]
	v_lshl_add_u64 v[114:115], v[114:115], 0, v[128:129]
	v_lshl_add_u64 v[116:117], v[140:141], 2, s[10:11]
	v_fmamk_f32 v112, v112, 0x3a800000, v178
	v_rsq_f32_e32 v112, v112
	s_nop 0
	v_pk_mul_f32 v[108:109], v[108:109], v[112:113] op_sel_hi:[1,0]
	v_pk_mul_f32 v[110:111], v[110:111], v[112:113] op_sel_hi:[1,0]
	v_pk_mul_f32 v[104:105], v[104:105], v[112:113] op_sel_hi:[1,0]
	v_pk_mul_f32 v[106:107], v[106:107], v[112:113] op_sel_hi:[1,0]
	v_pk_mul_f32 v[118:119], v[100:101], v[112:113] op_sel_hi:[1,0]
	v_pk_mul_f32 v[120:121], v[102:103], v[112:113] op_sel_hi:[1,0]
	v_pk_mul_f32 v[122:123], v[96:97], v[112:113] op_sel_hi:[1,0]
	v_pk_mul_f32 v[112:113], v[98:99], v[112:113] op_sel_hi:[1,0]
	v_pk_mul_f32 v[98:99], v[14:15], v[110:111]
	v_pk_mul_f32 v[96:97], v[12:13], v[108:109]
	v_pk_mul_f32 v[102:103], v[10:11], v[106:107]
	v_pk_mul_f32 v[100:101], v[8:9], v[104:105]
	v_pk_mul_f32 v[106:107], v[6:7], v[120:121]
	v_pk_mul_f32 v[104:105], v[4:5], v[118:119]
	v_pk_mul_f32 v[110:111], v[2:3], v[112:113]
	v_pk_mul_f32 v[108:109], v[0:1], v[122:123]
	global_store_dwordx4 v[114:115], v[96:99], off
	global_store_dwordx4 v[114:115], v[100:103], off offset:64
	global_store_dwordx4 v[114:115], v[104:107], off offset:512
	global_store_dwordx4 v[114:115], v[108:111], off offset:576
	v_mov_b32_e32 v96, v184
	v_lshl_add_u64 v[98:99], s[66:67], 0, v[138:139]
	v_lshl_add_u64 v[98:99], v[98:99], 0, v[128:129]
	v_lshl_add_u64 v[100:101], v[144:145], 2, s[10:11]
	v_fmamk_f32 v96, v96, 0x3a800000, v178
	v_rsq_f32_e32 v96, v96
	s_nop 0
	v_pk_mul_f32 v[92:93], v[92:93], v[96:97] op_sel_hi:[1,0]
	v_pk_mul_f32 v[94:95], v[94:95], v[96:97] op_sel_hi:[1,0]
	v_pk_mul_f32 v[88:89], v[88:89], v[96:97] op_sel_hi:[1,0]
	v_pk_mul_f32 v[90:91], v[90:91], v[96:97] op_sel_hi:[1,0]
	v_pk_mul_f32 v[102:103], v[84:85], v[96:97] op_sel_hi:[1,0]
	v_pk_mul_f32 v[104:105], v[86:87], v[96:97] op_sel_hi:[1,0]
	v_pk_mul_f32 v[106:107], v[80:81], v[96:97] op_sel_hi:[1,0]
	v_pk_mul_f32 v[96:97], v[82:83], v[96:97] op_sel_hi:[1,0]
	v_pk_mul_f32 v[82:83], v[14:15], v[94:95]
	v_pk_mul_f32 v[80:81], v[12:13], v[92:93]
	v_pk_mul_f32 v[86:87], v[10:11], v[90:91]
	v_pk_mul_f32 v[84:85], v[8:9], v[88:89]
	v_pk_mul_f32 v[90:91], v[6:7], v[104:105]
	v_pk_mul_f32 v[88:89], v[4:5], v[102:103]
	v_pk_mul_f32 v[94:95], v[2:3], v[96:97]
	v_pk_mul_f32 v[92:93], v[0:1], v[106:107]
	global_store_dwordx4 v[98:99], v[80:83], off
	global_store_dwordx4 v[98:99], v[84:87], off offset:64
	global_store_dwordx4 v[98:99], v[88:91], off offset:512
	global_store_dwordx4 v[98:99], v[92:95], off offset:576
	v_mov_b32_e32 v80, v185
	v_lshl_add_u64 v[82:83], s[66:67], 0, v[142:143]
	v_lshl_add_u64 v[82:83], v[82:83], 0, v[128:129]
	v_fmamk_f32 v80, v80, 0x3a800000, v178
	v_rsq_f32_e32 v80, v80
	s_nop 0
	v_pk_mul_f32 v[84:85], v[146:147], v[80:81] op_sel_hi:[1,0]
	v_pk_mul_f32 v[78:79], v[78:79], v[80:81] op_sel_hi:[1,0]
	v_pk_mul_f32 v[76:77], v[76:77], v[80:81] op_sel_hi:[1,0]
	v_pk_mul_f32 v[74:75], v[74:75], v[80:81] op_sel_hi:[1,0]
	v_pk_mul_f32 v[86:87], v[68:69], v[80:81] op_sel_hi:[1,0]
	v_pk_mul_f32 v[88:89], v[70:71], v[80:81] op_sel_hi:[1,0]
	v_pk_mul_f32 v[90:91], v[64:65], v[80:81] op_sel_hi:[1,0]
	v_pk_mul_f32 v[80:81], v[66:67], v[80:81] op_sel_hi:[1,0]
	v_pk_mul_f32 v[66:67], v[14:15], v[78:79]
	v_pk_mul_f32 v[64:65], v[12:13], v[84:85]
	v_pk_mul_f32 v[70:71], v[10:11], v[74:75]
	v_pk_mul_f32 v[68:69], v[8:9], v[76:77]
	v_pk_mul_f32 v[76:77], v[6:7], v[88:89]
	v_pk_mul_f32 v[74:75], v[4:5], v[86:87]
	v_pk_mul_f32 v[80:81], v[2:3], v[80:81]
	v_pk_mul_f32 v[78:79], v[0:1], v[90:91]
	global_store_dwordx4 v[82:83], v[64:67], off
	global_store_dwordx4 v[82:83], v[68:71], off offset:64
	global_store_dwordx4 v[82:83], v[74:77], off offset:512
	global_store_dwordx4 v[82:83], v[78:81], off offset:576
	v_mov_b32_e32 v64, v186
	v_lshl_add_u64 v[66:67], s[66:67], 0, v[72:73]
	v_lshl_add_u64 v[66:67], v[66:67], 0, v[128:129]
	v_fmamk_f32 v64, v64, 0x3a800000, v178
	v_rsq_f32_e32 v64, v64
	s_nop 0
	v_pk_mul_f32 v[68:69], v[148:149], v[64:65] op_sel_hi:[1,0]
	v_pk_mul_f32 v[62:63], v[62:63], v[64:65] op_sel_hi:[1,0]
	v_pk_mul_f32 v[60:61], v[60:61], v[64:65] op_sel_hi:[1,0]
	v_pk_mul_f32 v[58:59], v[58:59], v[64:65] op_sel_hi:[1,0]
	v_pk_mul_f32 v[70:71], v[52:53], v[64:65] op_sel_hi:[1,0]
	v_pk_mul_f32 v[72:73], v[54:55], v[64:65] op_sel_hi:[1,0]
	v_pk_mul_f32 v[74:75], v[48:49], v[64:65] op_sel_hi:[1,0]
	v_pk_mul_f32 v[64:65], v[50:51], v[64:65] op_sel_hi:[1,0]
	v_pk_mul_f32 v[50:51], v[14:15], v[62:63]
	v_pk_mul_f32 v[48:49], v[12:13], v[68:69]
	v_pk_mul_f32 v[54:55], v[10:11], v[58:59]
	v_pk_mul_f32 v[52:53], v[8:9], v[60:61]
	v_pk_mul_f32 v[60:61], v[6:7], v[72:73]
	v_pk_mul_f32 v[58:59], v[4:5], v[70:71]
	v_pk_mul_f32 v[64:65], v[2:3], v[64:65]
	v_pk_mul_f32 v[62:63], v[0:1], v[74:75]
	global_store_dwordx4 v[66:67], v[48:51], off
	global_store_dwordx4 v[66:67], v[52:55], off offset:64
	global_store_dwordx4 v[66:67], v[58:61], off offset:512
	global_store_dwordx4 v[66:67], v[62:65], off offset:576
	v_mov_b32_e32 v48, v187
	v_lshl_add_u64 v[50:51], s[66:67], 0, v[56:57]
	v_lshl_add_u64 v[50:51], v[50:51], 0, v[128:129]
	v_fmamk_f32 v48, v48, 0x3a800000, v178
	v_rsq_f32_e32 v48, v48
	s_nop 0
	v_pk_mul_f32 v[52:53], v[150:151], v[48:49] op_sel_hi:[1,0]
	v_pk_mul_f32 v[46:47], v[46:47], v[48:49] op_sel_hi:[1,0]
	v_pk_mul_f32 v[44:45], v[44:45], v[48:49] op_sel_hi:[1,0]
	v_pk_mul_f32 v[42:43], v[42:43], v[48:49] op_sel_hi:[1,0]
	v_pk_mul_f32 v[54:55], v[36:37], v[48:49] op_sel_hi:[1,0]
	v_pk_mul_f32 v[56:57], v[38:39], v[48:49] op_sel_hi:[1,0]
	v_pk_mul_f32 v[58:59], v[32:33], v[48:49] op_sel_hi:[1,0]
	v_pk_mul_f32 v[48:49], v[34:35], v[48:49] op_sel_hi:[1,0]
	v_pk_mul_f32 v[34:35], v[14:15], v[46:47]
	v_pk_mul_f32 v[32:33], v[12:13], v[52:53]
	v_pk_mul_f32 v[38:39], v[10:11], v[42:43]
	v_pk_mul_f32 v[36:37], v[8:9], v[44:45]
	v_pk_mul_f32 v[44:45], v[6:7], v[56:57]
	v_pk_mul_f32 v[42:43], v[4:5], v[54:55]
	v_pk_mul_f32 v[48:49], v[2:3], v[48:49]
	v_pk_mul_f32 v[46:47], v[0:1], v[58:59]
	global_store_dwordx4 v[50:51], v[32:35], off
	global_store_dwordx4 v[50:51], v[36:39], off offset:64
	global_store_dwordx4 v[50:51], v[42:45], off offset:512
	global_store_dwordx4 v[50:51], v[46:49], off offset:576
	v_mov_b32_e32 v32, v188
	v_lshl_add_u64 v[34:35], s[66:67], 0, v[40:41]
	v_lshl_add_u64 v[34:35], v[34:35], 0, v[128:129]
	v_fmamk_f32 v32, v32, 0x3a800000, v178
	v_rsq_f32_e32 v32, v32
	s_nop 0
	v_pk_mul_f32 v[36:37], v[152:153], v[32:33] op_sel_hi:[1,0]
	v_pk_mul_f32 v[30:31], v[30:31], v[32:33] op_sel_hi:[1,0]
	v_pk_mul_f32 v[28:29], v[28:29], v[32:33] op_sel_hi:[1,0]
	v_pk_mul_f32 v[26:27], v[26:27], v[32:33] op_sel_hi:[1,0]
	v_pk_mul_f32 v[38:39], v[20:21], v[32:33] op_sel_hi:[1,0]
	v_pk_mul_f32 v[40:41], v[22:23], v[32:33] op_sel_hi:[1,0]
	v_pk_mul_f32 v[42:43], v[16:17], v[32:33] op_sel_hi:[1,0]
	v_pk_mul_f32 v[32:33], v[18:19], v[32:33] op_sel_hi:[1,0]
	v_pk_mul_f32 v[18:19], v[14:15], v[30:31]
	v_pk_mul_f32 v[16:17], v[12:13], v[36:37]
	v_pk_mul_f32 v[22:23], v[10:11], v[26:27]
	v_pk_mul_f32 v[20:21], v[8:9], v[28:29]
	v_pk_mul_f32 v[28:29], v[6:7], v[40:41]
	v_pk_mul_f32 v[26:27], v[4:5], v[38:39]
	v_pk_mul_f32 v[32:33], v[2:3], v[32:33]
	v_pk_mul_f32 v[30:31], v[0:1], v[42:43]
	global_store_dwordx4 v[34:35], v[16:19], off
	global_store_dwordx4 v[34:35], v[20:23], off offset:64
	global_store_dwordx4 v[34:35], v[26:29], off offset:512
	global_store_dwordx4 v[34:35], v[30:33], off offset:576
	v_mov_b32_e32 v16, v189
	v_lshl_add_u64 v[18:19], s[66:67], 0, v[24:25]
	v_lshl_add_u64 v[18:19], v[18:19], 0, v[128:129]
	v_fmac_f32_e32 v178, 0x3a800000, v16
	v_rsq_f32_e32 v16, v178
	s_nop 0
	v_pk_mul_f32 v[20:21], v[168:169], v[16:17] op_sel_hi:[1,0]
	v_pk_mul_f32 v[22:23], v[166:167], v[16:17] op_sel_hi:[1,0]
	v_pk_mul_f32 v[24:25], v[164:165], v[16:17] op_sel_hi:[1,0]
	v_pk_mul_f32 v[26:27], v[162:163], v[16:17] op_sel_hi:[1,0]
	v_pk_mul_f32 v[28:29], v[160:161], v[16:17] op_sel_hi:[1,0]
	v_pk_mul_f32 v[30:31], v[158:159], v[16:17] op_sel_hi:[1,0]
	v_pk_mul_f32 v[32:33], v[156:157], v[16:17] op_sel_hi:[1,0]
	v_pk_mul_f32 v[16:17], v[154:155], v[16:17] op_sel_hi:[1,0]
	v_pk_mul_f32 v[14:15], v[14:15], v[22:23]
	v_pk_mul_f32 v[12:13], v[12:13], v[20:21]
	v_pk_mul_f32 v[10:11], v[10:11], v[26:27]
	v_pk_mul_f32 v[8:9], v[8:9], v[24:25]
	v_pk_mul_f32 v[6:7], v[6:7], v[30:31]
	v_pk_mul_f32 v[4:5], v[4:5], v[28:29]
	v_pk_mul_f32 v[2:3], v[2:3], v[16:17]
	v_pk_mul_f32 v[0:1], v[0:1], v[32:33]
	global_store_dwordx4 v[18:19], v[12:15], off
	global_store_dwordx4 v[18:19], v[8:11], off offset:64
	global_store_dwordx4 v[18:19], v[4:7], off offset:512
	global_store_dwordx4 v[18:19], v[0:3], off offset:576
	s_bfe_u32 s0, s79, 0x20006
	s_cmp_lg_u32 s0, 0
	s_cbranch_scc1 .Ls3_done
	s_lshl_b32 s0, s72, 8
	s_add_u32 s0, s68, s0
	s_addc_u32 s1, s69, 0
	v_mov_b32_e32 v9, 0x48000
	s_mov_b32 s3, 0x100000
